# v13 plus GLA prompt: all 8 segment-total LDS reads of the in-chunk prefix issued up front (renamed destinations, counted lgkmcnt)
# speedup vs baseline: 1.0160x; 1.0160x over previous
; #define LAS __attribute__((address_space(3)))
; #define LBAR() do { asm volatile("s_waitcnt lgkmcnt(0)" ::: "memory"); __builtin_amdgcn_s_barrier(); asm volatile("" ::: "memory"); } while (0)
; __device__ __forceinline__ void gla_prompt_item(Frame& F, int b, int h) {
;     ...
;         const size_t t0 = tokb + 64 * (size_t)n;
;         f32x2 cs[4]; cs[0] = lg[0];
; #pragma unroll
;         for (int i = 1; i < 4; ++i) cs[i] = cs[i - 1] + lg[i];
;         *(LAS f32x2*)(L + G_TOT + (seg * 64 + 2 * kp) * 4) = cs[3];
; #pragma unroll
;         for (int i = 0; i < 2; ++i) { const int p_ = tid + 512 * i, row_ = p_ >> 4, c_ = p_ & 15; *(LAS v4u*)(L + G_V + row_ * G_VP + c_ * 16) = vv[i]; }
;         LBAR();
;         if (n > 0) {
; #pragma unroll
;             for (int i = 0; i < 2; ++i) *(v4u*)(MIX + (t0 - 64 + et) * DM + DA + h * 128 + 16 * evc + 8 * i) = outp[i];
;         }
;         f32x2 pre = {0.f, 0.f}, tot = {0.f, 0.f};
; #pragma unroll
;         for (int s = 0; s < 16; ++s) { const f32x2 v = *(const LAS f32x2*)(L + G_TOT + (s * 64 + 2 * kp) * 4); if (s < seg) pre += v; tot += v; }
;     ...
;         for (int i = 0; i < 2; ++i) gg[i] = *(const v4u*)(GBp + (t0 + et) * 512 + h * 128 + 16 * evc + 8 * i);
;         if (n + 1 < SEQ / 64 && var != 2) GLA_LOAD(n + 1);
.LBB0_595:
	v_pk_add_f32 v[140:141], v[80:81], v[78:79]
	v_add_u32_e32 v42, 0, v1
	v_pk_add_f32 v[142:143], v[140:141], v[82:83]
	v_add_u32_e32 v66, 0x13800, v42
	v_pk_add_f32 v[144:145], v[142:143], v[84:85]
	ds_write_b64 v99, v[144:145]
	ds_write_b128 v96, v[18:21] offset:18432
	ds_write_b128 v97, v[22:25] offset:18432
	s_waitcnt lgkmcnt(0)
	s_barrier
	v_lshl_add_u64 v[54:55], s[58:59], 0, v[94:95]
	v_add_u32_e32 v139, 0x800, v66
	ds_read2_b64 v[42:45], v66 offset1:32
	ds_read2_b64 v[154:157], v66 offset0:64 offset1:96
	ds_read2_b64 v[158:161], v66 offset0:128 offset1:160
	ds_read2_b64 v[162:165], v66 offset0:192 offset1:224
	ds_read2_b64 v[166:169], v139 offset1:32
	ds_read2_b64 v[170:173], v139 offset0:64 offset1:96
	ds_read2_b64 v[176:179], v139 offset0:128 offset1:160
	ds_read2_b64 v[180:183], v139 offset0:192 offset1:224
	v_add_co_u32_e32 v54, vcc, s33, v54
	s_nop 0
	v_addc_co_u32_e32 v55, vcc, 0, v55, vcc
	global_store_dwordx4 v[54:55], v[50:53], off offset:1024
	global_store_dwordx4 v[54:55], v[46:49], off offset:1040
	v_lshl_add_u64 v[212:213], s[58:59], 0, v[92:93]
	v_lshl_add_u64 v[214:215], v[212:213], 0, s[74:75]
	v_add_co_u32_e32 v212, vcc, 0x27c10000, v212
	s_nop 1
	v_addc_co_u32_e32 v213, vcc, 0, v213, vcc
	global_load_dwordx4 v[220:223], v[212:213], off
	global_load_dwordx4 v[224:227], v[214:215], off offset:16
	s_cmp_eq_u32 s1, 1
	s_cbranch_scc1 .Lgla_nopf
	v_lshl_add_u64 v[212:213], s[58:59], 0, v[90:91]
	v_add_co_u32_e32 v214, vcc, 0x1f410000, v212
	s_nop 1
	v_addc_co_u32_e32 v215, vcc, 0, v213, vcc
	v_add_co_u32_e32 v216, vcc, 0x16c10000, v212
	s_nop 1
	v_addc_co_u32_e32 v217, vcc, 0, v213, vcc
	v_add_co_u32_e32 v218, vcc, 0x18e10000, v212
	s_nop 1
	v_addc_co_u32_e32 v219, vcc, 0, v213, vcc
	global_load_dword v192, v[214:215], off
	global_load_dword v196, v[216:217], off
	global_load_dword v193, v[214:215], off offset:512
	global_load_dword v197, v[216:217], off offset:512
	global_load_dword v194, v[214:215], off offset:1024
	global_load_dword v198, v[216:217], off offset:1024
	global_load_dword v199, v[216:217], off offset:1536
	global_load_dword v195, v[214:215], off offset:1536
	v_lshl_add_u64 v[212:213], s[58:59], 0, v[88:89]
	v_lshl_add_u64 v[214:215], s[58:59], 0, v[86:87]
	global_load_dwordx4 v[200:203], v[212:213], off
	global_load_dwordx4 v[204:207], v[214:215], off
	global_load_dword v208, v[218:219], off
	global_load_dword v209, v[218:219], off offset:512
	global_load_dword v210, v[218:219], off offset:1024
	global_load_dword v211, v[218:219], off offset:1536
; #define LAS __attribute__((address_space(3)))
; __device__ __forceinline__ unsigned pk2(float lo, float hi) { typedef float f2 __attribute__((ext_vector_type(2))); typedef __bf16 b2 __attribute__((ext_vector_type(2))); f2 v = {lo, hi}; b2 b = __builtin_convertvector(v, b2); return __builtin_bit_cast(unsigned, b); }
; __device__ __forceinline__ float fast_exp(float x) { return __builtin_amdgcn_exp2f(x * LOG2E); }
; __device__ __forceinline__ void gla_prompt_item(Frame& F, int b, int h) {
;     ...
;         f32x2 pre = {0.f, 0.f}, tot = {0.f, 0.f};
; #pragma unroll
;         for (int s = 0; s < 16; ++s) { const f32x2 v = *(const LAS f32x2*)(L + G_TOT + (s * 64 + 2 * kp) * 4); if (s < seg) pre += v; tot += v; }
; #pragma unroll
;         for (int i = 0; i < 4; ++i) {
;             f32x2 bb = pre + cs[i]; bb.x = fmaxf(bb.x, -80.f); bb.y = fmaxf(bb.y, -80.f);
;             const float ep0 = fast_exp(bb.x), ep1 = fast_exp(bb.y), em0 = fast_exp(-bb.x), em1 = fast_exp(-bb.y);
;             const int t = 4 * seg + i;
;             *(LAS unsigned*)(L + G_QT + t * G_RP + kp * 4) = pk2(bflo(qv[i]) * ep0, bfhi(qv[i]) * ep1);
;             *(LAS unsigned*)(L + G_KT + t * G_RP + kp * 4) = pk2(bflo(kv[i]) * em0, bfhi(kv[i]) * em1);
;         }
;         if (seg == 0) { f32x2 dd; dd.x = fast_exp(fmaxf(tot.x, -80.f)); dd.y = fast_exp(fmaxf(tot.y, -80.f)); *(LAS f32x2*)(L + G_D + 2 * kp * 4) = dd; }
.Lgla_nopf:
	s_waitcnt lgkmcnt(7)
	v_pk_add_f32 v[42:43], v[42:43], 0 op_sel_hi:[1,0]
	v_lshlrev_b32_e32 v152, 16, v103
	v_cndmask_b32_e64 v51, 0, v43, s[4:5]
	v_cndmask_b32_e64 v50, 0, v42, s[4:5]
	v_pk_add_f32 v[52:53], v[44:45], v[50:51]
	v_and_b32_e32 v153, 0xffff0000, v103
	v_cndmask_b32_e64 v55, v51, v53, s[6:7]
	v_cndmask_b32_e64 v54, v50, v52, s[6:7]
	s_waitcnt lgkmcnt(6)
	v_pk_add_f32 v[56:57], v[154:155], v[54:55]
	s_nop 0
	v_cndmask_b32_e64 v55, v55, v57, s[8:9]
	v_cndmask_b32_e64 v54, v54, v56, s[8:9]
	v_pk_add_f32 v[56:57], v[156:157], v[54:55]
	s_nop 0
	v_cndmask_b32_e64 v59, v55, v57, s[10:11]
	v_cndmask_b32_e64 v58, v54, v56, s[10:11]
	s_waitcnt lgkmcnt(5)
	v_pk_add_f32 v[60:61], v[158:159], v[58:59]
	s_nop 0
	v_cndmask_b32_e64 v59, v59, v61, s[12:13]
	v_cndmask_b32_e64 v58, v58, v60, s[12:13]
	v_pk_add_f32 v[60:61], v[160:161], v[58:59]
	s_nop 0
	v_cndmask_b32_e64 v63, v59, v61, s[14:15]
	v_cndmask_b32_e64 v62, v58, v60, s[14:15]
	s_waitcnt lgkmcnt(4)
	v_pk_add_f32 v[64:65], v[162:163], v[62:63]
	s_nop 0
	v_cndmask_b32_e64 v63, v63, v65, s[16:17]
	v_cndmask_b32_e64 v62, v62, v64, s[16:17]
	v_pk_add_f32 v[64:65], v[164:165], v[62:63]
	s_nop 0
	v_cndmask_b32_e64 v67, v63, v65, s[18:19]
	v_cndmask_b32_e64 v66, v62, v64, s[18:19]
	s_waitcnt lgkmcnt(3)
	v_pk_add_f32 v[68:69], v[166:167], v[66:67]
	s_nop 0
	v_cndmask_b32_e64 v67, v67, v69, s[20:21]
	v_cndmask_b32_e64 v66, v66, v68, s[20:21]
	v_pk_add_f32 v[68:69], v[168:169], v[66:67]
	s_nop 0
	v_cndmask_b32_e64 v71, v67, v69, s[22:23]
	v_cndmask_b32_e64 v70, v66, v68, s[22:23]
	s_waitcnt lgkmcnt(2)
	v_pk_add_f32 v[72:73], v[170:171], v[70:71]
	s_nop 0
	v_cndmask_b32_e64 v71, v71, v73, s[24:25]
	v_cndmask_b32_e64 v70, v70, v72, s[24:25]
	v_pk_add_f32 v[72:73], v[172:173], v[70:71]
	s_nop 0
	v_cndmask_b32_e64 v147, v71, v73, s[26:27]
	v_cndmask_b32_e64 v146, v70, v72, s[26:27]
	s_waitcnt lgkmcnt(1)
	v_pk_add_f32 v[148:149], v[176:177], v[146:147]
	s_nop 0
	v_cndmask_b32_e64 v147, v147, v149, s[28:29]
	v_cndmask_b32_e64 v146, v146, v148, s[28:29]
	v_pk_add_f32 v[148:149], v[178:179], v[146:147]
	s_nop 0
	v_cndmask_b32_e64 v147, v147, v149, s[30:31]
	v_cndmask_b32_e64 v146, v146, v148, s[30:31]
	s_waitcnt lgkmcnt(0)
	v_pk_add_f32 v[148:149], v[180:181], v[146:147]
	s_nop 0
	v_cndmask_b32_e64 v147, v147, v149, s[34:35]
	v_cndmask_b32_e64 v146, v146, v148, s[34:35]
	v_pk_add_f32 v[148:149], v[182:183], v[146:147]
	s_nop 0
	v_cndmask_b32_e64 v147, v147, v149, s[36:37]
	v_cndmask_b32_e64 v146, v146, v148, s[36:37]
	v_pk_add_f32 v[148:149], v[146:147], v[78:79]
	v_pk_add_f32 v[140:141], v[140:141], v[146:147]
	v_max_f32_e32 v139, 0xc2a00000, v148
	v_max_f32_e32 v151, 0xc2a00000, v149
	v_mul_f32_e32 v148, 0x3fb8aa3b, v139
	v_mul_f32_e32 v149, 0x3fb8aa3b, v151
	v_exp_f32_e32 v148, v148
	v_exp_f32_e32 v149, v149
	v_mul_f32_e32 v139, 0xbfb8aa3b, v139
	v_exp_f32_e32 v150, v139
	v_mul_f32_e32 v139, 0xbfb8aa3b, v151
	v_exp_f32_e32 v151, v139
	v_pk_mul_f32 v[148:149], v[148:149], v[152:153]
	s_nop 0
	v_cvt_pk_bf16_f32 v139, v148, v149
	v_lshlrev_b32_e32 v148, 16, v110
	v_and_b32_e32 v149, 0xffff0000, v110
	v_pk_mul_f32 v[148:149], v[150:151], v[148:149]
	v_lshlrev_b32_e32 v150, 16, v104
	v_cvt_pk_bf16_f32 v152, v148, v149
	v_max_f32_e32 v148, 0xc2a00000, v140
	v_max_f32_e32 v149, 0xc2a00000, v141
	v_mul_f32_e32 v140, 0x3fb8aa3b, v148
	v_mul_f32_e32 v141, 0x3fb8aa3b, v149
	v_exp_f32_e32 v140, v140
	v_exp_f32_e32 v141, v141
	v_mul_f32_e32 v148, 0xbfb8aa3b, v148
	v_mul_f32_e32 v149, 0xbfb8aa3b, v149
	v_exp_f32_e32 v148, v148
	v_exp_f32_e32 v149, v149
	v_and_b32_e32 v151, 0xffff0000, v104
	v_pk_mul_f32 v[140:141], v[140:141], v[150:151]
	v_add_u32_e32 v150, 0x2400, v98
	v_cvt_pk_bf16_f32 v140, v140, v141
	ds_write2_b32 v98, v139, v140 offset1:36
	v_lshlrev_b32_e32 v140, 16, v111
	v_and_b32_e32 v141, 0xffff0000, v111
	v_pk_mul_f32 v[140:141], v[148:149], v[140:141]
	v_lshlrev_b32_e32 v148, 16, v107
	v_cvt_pk_bf16_f32 v139, v140, v141
	v_pk_add_f32 v[140:141], v[142:143], v[146:147]
	ds_write2_b32 v150, v152, v139 offset1:36
	v_max_f32_e32 v139, 0xc2a00000, v140
	v_max_f32_e32 v143, 0xc2a00000, v141
	v_mul_f32_e32 v140, 0x3fb8aa3b, v139
	v_mul_f32_e32 v141, 0x3fb8aa3b, v143
	v_exp_f32_e32 v140, v140
	v_exp_f32_e32 v141, v141
	v_mul_f32_e32 v139, 0xbfb8aa3b, v139
	v_exp_f32_e32 v142, v139
	v_mul_f32_e32 v139, 0xbfb8aa3b, v143
	v_exp_f32_e32 v143, v139
	v_and_b32_e32 v149, 0xffff0000, v107
	v_pk_mul_f32 v[140:141], v[140:141], v[148:149]
	s_nop 0
	v_cvt_pk_bf16_f32 v139, v140, v141
	v_lshlrev_b32_e32 v140, 16, v112
	v_and_b32_e32 v141, 0xffff0000, v112
	v_pk_mul_f32 v[140:141], v[142:143], v[140:141]
	s_nop 0
	v_cvt_pk_bf16_f32 v148, v140, v141
	v_pk_add_f32 v[140:141], v[144:145], v[146:147]
	v_lshlrev_b32_e32 v144, 16, v109
	v_max_f32_e32 v142, 0xc2a00000, v140
	v_max_f32_e32 v143, 0xc2a00000, v141
	v_mul_f32_e32 v140, 0x3fb8aa3b, v142
	v_mul_f32_e32 v141, 0x3fb8aa3b, v143
	v_exp_f32_e32 v140, v140
	v_exp_f32_e32 v141, v141
	v_mul_f32_e32 v142, 0xbfb8aa3b, v142
	v_mul_f32_e32 v143, 0xbfb8aa3b, v143
	v_exp_f32_e32 v142, v142
	v_exp_f32_e32 v143, v143
	v_and_b32_e32 v145, 0xffff0000, v109
	v_pk_mul_f32 v[140:141], v[140:141], v[144:145]
	s_nop 0
	v_cvt_pk_bf16_f32 v140, v140, v141
	ds_write2_b32 v98, v139, v140 offset0:72 offset1:108
	v_lshlrev_b32_e32 v140, 16, v113
	v_and_b32_e32 v141, 0xffff0000, v113
	v_pk_mul_f32 v[140:141], v[142:143], v[140:141]
	s_nop 0
	v_cvt_pk_bf16_f32 v139, v140, v141
	ds_write2_b32 v150, v148, v139 offset0:72 offset1:108
	s_and_saveexec_b64 s[82:83], s[54:55]
	s_cbranch_execz .LBB0_597
	v_pk_add_f32 v[42:43], v[42:43], v[44:45]
	v_add_u32_e32 v44, 0x14800, v100
	v_pk_add_f32 v[42:43], v[42:43], v[154:155]
	s_nop 0
	v_pk_add_f32 v[42:43], v[42:43], v[156:157]
	s_nop 0
	v_pk_add_f32 v[42:43], v[42:43], v[158:159]
	s_nop 0
	v_pk_add_f32 v[42:43], v[42:43], v[160:161]
	s_nop 0
	v_pk_add_f32 v[42:43], v[42:43], v[162:163]
	s_nop 0
	v_pk_add_f32 v[42:43], v[42:43], v[164:165]
	s_nop 0
	v_pk_add_f32 v[42:43], v[42:43], v[166:167]
	s_nop 0
	v_pk_add_f32 v[42:43], v[42:43], v[168:169]
	s_nop 0
	v_pk_add_f32 v[42:43], v[42:43], v[170:171]
	s_nop 0
	v_pk_add_f32 v[42:43], v[42:43], v[172:173]
	s_nop 0
	v_pk_add_f32 v[42:43], v[42:43], v[176:177]
	s_nop 0
	v_pk_add_f32 v[42:43], v[42:43], v[178:179]
	s_nop 0
	v_pk_add_f32 v[42:43], v[42:43], v[180:181]
	s_nop 0
	v_pk_add_f32 v[42:43], v[42:43], v[182:183]
	s_nop 0
	v_max_f32_e32 v42, 0xc2a00000, v42
	v_max_f32_e32 v43, 0xc2a00000, v43
	v_mul_f32_e32 v42, 0x3fb8aa3b, v42
	v_mul_f32_e32 v43, 0x3fb8aa3b, v43
	v_exp_f32_e32 v42, v42
	v_exp_f32_e32 v43, v43
	ds_write_b64 v44, v[42:43]
